# DA unit head: K/V/Q tile-0 loads no longer wait behind the lambda parameter loads (counted waits instead of two vmcnt(0))
# speedup vs baseline: 1.1084x; 1.0014x over previous
; __device__ __forceinline__ float bflo(unsigned w) { return __uint_as_float(w << 16); }
; __device__ void da_unit(char* lds, const Params& p, int layer, int unit) {
;     ...
;     {
;         const float v1 = p.lq1[layer * 64 + lane] * p.lk1[layer * 64 + lane], v2 = p.lq2[layer * 64 + lane] * p.lk2[layer * 64 + lane];
;         float s1 = v1, s2 = v2;
; #pragma unroll
;         for (int s = 32; s >= 1; s >>= 1) { s1 += __shfl_xor(s1, s); s2 += __shfl_xor(s2, s); }
;         lam = __expf(s1) - __expf(s2) + p.lam_init[layer];
;     }
;     const int q0 = qb * 128 + qg * 32;
;     const size_t tokq = (size_t)b * SEQ + q0 + r;
;     bf16x8 qf[4];
; #pragma unroll
;     for (int t = 0; t < 4; ++t) {
;         const u32x4 w = *(const u32x4*)(p.z + ZS_QD + ((size_t)(bh * 2048 + q0 + r)) * 128 + c * 64 + t * 16 + h2 * 8);
;         u32x4 o;
;         o.x = cvt_pk_bf16(bflo(w.x) * qscale, bfhi(w.x) * qscale); o.y = cvt_pk_bf16(bflo(w.y) * qscale, bfhi(w.y) * qscale);
;         o.z = cvt_pk_bf16(bflo(w.z) * qscale, bfhi(w.z) * qscale); o.w = cvt_pk_bf16(bflo(w.w) * qscale, bfhi(w.w) * qscale);
;         qf[t] = __builtin_bit_cast(bf16x8, o);
;     }
;     f32x16 O[4], Bs;
; #pragma unroll
;     for (int k = 0; k < 4; ++k)
; #pragma unroll
;         for (int e = 0; e < 16; ++e) O[k][e] = 0.f;
; #pragma unroll
;     for (int e = 0; e < 16; ++e) Bs[e] = -slope2 * (float)(16 * (e >> 3) + (e & 7));
;     float mrow = -1e30f, lrow = 0.f;
;     const float qrel = (float)(8 * h2) - (float)(q0 + r);
;     const bf16_t* Kg = p.z + ZS_KD + ((size_t)bh * 2048) * 128 + tid * 8;
;     const bf16_t* Vg = p.vT + VS_VD + ((size_t)bh * 32) * 8192 + tid * 8;
;     const int kr_ = tid >> 4, kc_ = tid & 15, vr_ = tid >> 3, vc_ = tid & 7;
;     constexpr int NT = SEQ / 128;
;     auto tile_of = [&](int i) { return (i < NT - qb) ? (qb + i) : (NT - 1 - i); };
;     u32x4 rk[4], rv[4];
;     {
;         const int t0 = tile_of(0);
; #pragma unroll
;         for (int j = 0; j < 4; ++j) { rk[j] = *(const u32x4*)(Kg + (size_t)t0 * 16384 + j * 4096); rv[j] = *(const u32x4*)(Vg + (size_t)t0 * 16384 + j * 4096); }
;     }
;     __syncthreads();
; #pragma unroll
;     for (int j = 0; j < 4; ++j) {
;         *(u32x4*)(lds + (kr_ + 32 * j) * DA_KP + kc_ * 16) = rk[j];
;         *(u32x4*)(lds + DA_KBYTES + (j >> 1) * DA_VSUB + (vr_ + 64 * (j & 1)) * DA_VP + vc_ * 16) = rv[j];
;     }
.LBB0_475:
	s_and_b64 vcc, exec, s[0:1]
	s_cbranch_vccz .LBB0_451
	v_mov_b32_e32 v187, v245
	v_readlane_b32 s0, v255, 36
	v_and_b32_e32 v184, 63, v187
	s_bfe_u32 s14, s21, 0x40003
	v_or_b32_e32 v152, s0, v184
	v_readlane_b32 s0, v254, 60
	v_lshlrev_b64 v[0:1], 2, v[152:153]
	v_readlane_b32 s1, v254, 61
	v_readlane_b32 s2, v254, 62
	v_readlane_b32 s3, v254, 63
	v_lshl_add_u64 v[2:3], s[0:1], 0, v[0:1]
	global_load_dword v8, v[2:3], off
	v_lshl_add_u64 v[2:3], s[2:3], 0, v[0:1]
	global_load_dword v9, v[2:3], off
	v_readlane_b32 s4, v255, 0
	v_readlane_b32 s5, v255, 1
	v_readlane_b32 s6, v255, 2
	v_readlane_b32 s7, v255, 3
	v_lshl_add_u64 v[2:3], s[4:5], 0, v[0:1]
	global_load_dword v50, v[2:3], off
	v_lshl_add_u64 v[0:1], s[6:7], 0, v[0:1]
	global_load_dword v51, v[0:1], off
	s_lshl_b32 s0, s21, 2
	s_ashr_i32 s1, s21, 7
	s_and_b32 s2, s0, 28
	v_readfirstlane_b32 s3, v187
	s_and_b32 s12, s1, 3
	s_add_i32 s6, s2, s1
	s_bfe_u32 s13, s3, 0x20006
	s_lshl_b32 s0, s14, 7
	s_not_b32 s4, s12
	s_ashr_i32 s7, s6, 31
	s_lshl_b32 s5, s13, 5
	v_and_b32_e32 v0, 64, v240
	s_ashr_i32 s10, s3, 6
	s_lshl_b32 s1, s4, 1
	s_lshl_b32 s4, s6, 11
	s_lshl_b64 s[2:3], s[6:7], 19
	s_add_i32 s7, s5, s0
	v_xor_b32_e32 v1, 32, v240
	v_add_u32_e32 v52, 64, v0
	v_and_b32_e32 v147, 31, v187
	s_lshr_b32 s15, s10, 2
	s_add_i32 s4, s7, s4
	v_cmp_lt_i32_e32 vcc, v1, v52
	s_lshl_b32 s8, s15, 7
	v_or_b32_e32 v2, s4, v147
	v_readlane_b32 s4, v254, 18
	v_cndmask_b32_e32 v1, v240, v1, vcc
	v_lshlrev_b32_e32 v0, 3, v187
	s_add_u32 s4, s4, s2
	v_readlane_b32 s5, v254, 19
	v_lshlrev_b32_e32 v244, 2, v1
	v_ashrrev_i32_e32 v1, 31, v0
	s_addc_u32 s5, s5, s3
	v_lshlrev_b64 v[0:1], 1, v[0:1]
	s_add_u32 s2, s60, s2
	v_lshl_add_u64 v[148:149], s[4:5], 0, v[0:1]
	s_addc_u32 s3, s61, s3
	s_lshl_b32 s70, s14, 15
	v_lshl_add_u64 v[164:165], v[148:149], 0, s[70:71]
	v_lshl_add_u64 v[150:151], s[2:3], 0, v[0:1]
	v_add_co_u32_e32 v0, vcc, s47, v164
	s_movk_i32 s2, 0x4000
	s_nop 0
	v_addc_co_u32_e32 v1, vcc, 0, v165, vcc
	v_add_co_u32_e32 v4, vcc, s2, v164
	s_movk_i32 s3, 0x6000
	s_nop 0
	v_addc_co_u32_e32 v5, vcc, 0, v165, vcc
	v_add_co_u32_e32 v6, vcc, s3, v164
	v_lshl_add_u64 v[166:167], v[150:151], 0, s[70:71]
	s_nop 0
	v_addc_co_u32_e32 v7, vcc, 0, v165, vcc
	global_load_dwordx4 v[18:21], v[164:165], off
	global_load_dwordx4 v[22:25], v[166:167], off
	global_load_dwordx4 v[26:29], v[0:1], off
	v_add_co_u32_e32 v0, vcc, s47, v166
	global_load_dwordx4 v[30:33], v[4:5], off
	global_load_dwordx4 v[34:37], v[6:7], off
	v_ashrrev_i32_e32 v3, 31, v2
	v_addc_co_u32_e32 v1, vcc, 0, v167, vcc
	v_lshlrev_b64 v[2:3], 8, v[2:3]
	v_add_co_u32_e32 v4, vcc, s2, v166
	s_mov_b32 s9, s71
	v_bfe_u32 v188, v187, 5, 1
	v_lshl_add_u64 v[2:3], s[58:59], 0, v[2:3]
	v_addc_co_u32_e32 v5, vcc, 0, v167, vcc
	s_waitcnt vmcnt(5)
	v_mul_f32_e32 v6, v8, v9
	ds_bpermute_b32 v53, v244, v6
	global_load_dwordx4 v[38:41], v[0:1], off
	global_load_dwordx4 v[42:45], v[4:5], off
	v_lshlrev_b32_e32 v152, 4, v188
	v_lshl_add_u64 v[2:3], v[2:3], 0, s[8:9]
	v_lshl_add_u64 v[12:13], v[2:3], 0, v[152:153]
	s_waitcnt lgkmcnt(0)
	v_fmac_f32_e32 v53, v8, v9
	v_mul_f32_e32 v0, v50, v51
	ds_bpermute_b32 v54, v244, v0
	v_add_co_u32_e32 v0, vcc, s3, v166
	s_movk_i32 s3, 0x110
	s_nop 0
	v_addc_co_u32_e32 v1, vcc, 0, v167, vcc
	global_load_dwordx4 v[46:49], v[0:1], off
	global_load_dwordx4 v[8:11], v[12:13], off
	global_load_dwordx4 v[4:7], v[12:13], off offset:32
	s_nop 0
	global_load_dwordx4 v[0:3], v[12:13], off offset:64
	global_load_dwordx4 v[14:17], v[12:13], off offset:96
	v_xor_b32_e32 v12, 16, v240
	v_cmp_lt_i32_e32 vcc, v12, v52
	s_waitcnt lgkmcnt(0)
	v_fmac_f32_e32 v54, v50, v51
	v_xor_b32_e32 v50, 8, v240
	v_cndmask_b32_e32 v12, v240, v12, vcc
	v_lshlrev_b32_e32 v12, 2, v12
	ds_bpermute_b32 v13, v12, v53
	ds_bpermute_b32 v12, v12, v54
	v_cmp_lt_i32_e32 vcc, v50, v52
	s_lshl_b32 s2, s14, 14
	s_cmp_lt_i32 s10, 4
	v_cndmask_b32_e32 v50, v240, v50, vcc
	s_waitcnt lgkmcnt(1)
	v_add_f32_e32 v13, v53, v13
	s_waitcnt lgkmcnt(0)
	v_add_f32_e32 v12, v54, v12
	v_lshlrev_b32_e32 v50, 2, v50
	ds_bpermute_b32 v51, v50, v13
	ds_bpermute_b32 v50, v50, v12
	s_waitcnt lgkmcnt(0)
	s_barrier
	v_add_f32_e32 v13, v13, v51
	v_add_f32_e32 v12, v12, v50
	v_xor_b32_e32 v50, 4, v240
	v_cmp_lt_i32_e32 vcc, v50, v52
	s_nop 1
	v_cndmask_b32_e32 v50, v240, v50, vcc
	v_lshlrev_b32_e32 v50, 2, v50
	ds_bpermute_b32 v51, v50, v13
	ds_bpermute_b32 v50, v50, v12
	s_waitcnt lgkmcnt(1)
	v_add_f32_e32 v13, v13, v51
	s_waitcnt lgkmcnt(0)
	v_add_f32_e32 v12, v12, v50
	v_xor_b32_e32 v50, 2, v240
	v_cmp_lt_i32_e32 vcc, v50, v52
	s_nop 1
	v_cndmask_b32_e32 v50, v240, v50, vcc
	v_lshlrev_b32_e32 v50, 2, v50
	ds_bpermute_b32 v51, v50, v13
	ds_bpermute_b32 v50, v50, v12
	s_waitcnt lgkmcnt(1)
	v_add_f32_e32 v170, v13, v51
	s_waitcnt lgkmcnt(0)
	v_add_f32_e32 v171, v12, v50
	v_xor_b32_e32 v12, 1, v240
	v_cmp_lt_i32_e32 vcc, v12, v52
	v_lshrrev_b32_e32 v13, 3, v187
	v_lshlrev_b32_e32 v50, 4, v187
	v_cndmask_b32_e32 v12, v240, v12, vcc
	v_lshlrev_b32_e32 v12, 2, v12
	ds_bpermute_b32 v172, v12, v170
	ds_bpermute_b32 v173, v12, v171
	v_lshrrev_b32_e32 v12, 4, v187
	v_mul_lo_u32 v182, v12, s3
	s_movk_i32 s3, 0x90
	v_and_b32_e32 v180, 0xf0, v50
	v_mul_lo_u32 v183, v13, s3
	v_add_u32_e32 v51, 0, v180
	v_and_b32_e32 v181, 0x70, v50
	v_add_u32_e32 v12, 0, v183
	v_add_u32_e32 v189, v51, v182
	v_add_u32_e32 v190, v12, v181
	s_waitcnt vmcnt(7)
	ds_write_b128 v189, v[18:21]
	ds_write_b128 v190, v[22:25] offset:34816
	ds_write_b128 v189, v[26:29] offset:8704
	s_waitcnt vmcnt(6)
	ds_write_b128 v190, v[38:41] offset:44032
	ds_write_b128 v189, v[30:33] offset:17408
	s_waitcnt vmcnt(5)
	ds_write_b128 v190, v[42:45] offset:53248
	ds_write_b128 v189, v[34:37] offset:26112
	s_waitcnt vmcnt(4)
	ds_write_b128 v190, v[46:49] offset:62464
	s_waitcnt lgkmcnt(0)
	s_barrier
	s_cbranch_scc1 .LBB0_478
	s_setprio 1
